# bit3 workgroups run the PLE projections before S5 pass C (P3 -> P2 -> late) so pass C meets less of the other half's streaming
# speedup vs baseline: 1.0065x; 1.0050x over previous
.LBB0_253:
	s_cmp_lt_i32 s8, 3
	s_cselect_b64 s[0:1], -1, 0
	s_cmp_gt_i32 s9, 2
	s_cselect_b64 s[4:5], -1, 0
	s_and_b64 s[0:1], s[0:1], s[4:5]
	s_andn2_b64 vcc, exec, s[0:1]
	s_cbranch_vccnz .LBB0_284
	s_bitcmp1_b32 s2, 3
	s_cbranch_scc0 .Lp2_x
	s_mov_b32 s99, 2
	s_branch .LBB0_284
.Lp2_x:
	s_mov_b32 s99, 0
	s_branch .Lp0_body

.LBB0_283:
	s_waitcnt lgkmcnt(0)
	s_barrier
	s_bitcmp1_b32 s2, 3
	s_cbranch_scc0 .LBB0_284
	s_mov_b32 s99, 0
	s_waitcnt vmcnt(0)
	s_branch .Lp0_body

.LBB0_327:
	s_bitcmp1_b32 s2, 3
	s_cbranch_scc0 .Lp3_done
	s_cmp_eq_u32 s99, 2
	s_cbranch_scc0 .Lp3_done
	s_mov_b32 s99, 3
	s_waitcnt vmcnt(0) lgkmcnt(0)
	s_barrier
	s_branch .Lp2_body
